# 5120 weight items per recurrence phase moved to the streamer WGs (5 per wave; more margin in the idle slot than 6144)
# speedup vs baseline: 1.0048x; 1.0008x over previous
; #define LAS __attribute__((address_space(3)))
; __global__ void __launch_bounds__(NTHR, 2) mega(const Args a) {
;     extern __shared__ __attribute__((aligned(16))) unsigned char lds_raw[];
;     LAS unsigned char* lds = (LAS unsigned char*)lds_raw;
;     const int wg0 = blockIdx.x, nwg0 = gridDim.x, tid = threadIdx.x;
;     for (int u = tid; u < (LDS_BYTES - LDSCTL_OFF) / 4; u += NTHR) ((LAS unsigned*)(lds + LDSCTL_OFF))[u] = 0u;
;     __syncthreads();
;     if (tid == 0) { const unsigned long long* src = (const unsigned long long*)&a.p;
; #pragma unroll
;         for (int i = 0; i < 25; ++i) *(LAS unsigned long long*)(lds + LDS_P_OFF + 8 * i) = src[i]; }
;     __syncthreads();
_Z4mega4Args:
	v_mov_b32_e32 v250, 0
	s_mov_b32 s3, 0x1d700
	v_writelane_b32 v250, s3, 2
	s_mov_b32 s3, 0x1d6ff
	v_writelane_b32 v250, s3, 3
	s_add_u32 s4, s0, 0xd0
	s_addc_u32 s5, s1, 0
	s_movk_i32 s3, 0x200
	v_writelane_b32 v249, s4, 0
	v_cmp_gt_u32_e32 vcc, s3, v0
	s_nop 0
	v_writelane_b32 v249, s5, 1
	s_and_saveexec_b64 s[6:7], vcc
	v_lshl_add_u32 v1, v0, 2, 0
	v_add_u32_e32 v1, 0x23800, v1
	v_mov_b32_e32 v2, 0
	ds_write_b32 v1, v2
	s_or_b64 exec, exec, s[6:7]
	s_waitcnt lgkmcnt(0)
	s_barrier
	v_cmp_eq_u32_e64 s[4:5], 0, v0
	s_mov_b64 s[22:23], exec
	s_nop 0
	v_writelane_b32 v249, s4, 2
	s_nop 1
	v_writelane_b32 v249, s5, 3
	s_and_b64 s[4:5], s[22:23], s[4:5]
	s_mov_b64 exec, s[4:5]
	s_cbranch_execz .LBB0_4
	s_load_dwordx16 s[4:19], s[0:1], 0x0
	s_add_i32 s20, 0, 0x23900
	s_load_dwordx16 s[48:63], s[0:1], 0x40
	v_mov_b32_e32 v1, s20
	s_add_i32 s20, 0, 0x23970
	s_waitcnt lgkmcnt(0)
	v_mov_b32_e32 v2, s4
	v_mov_b32_e32 v3, s5
	v_mov_b32_e32 v4, s6
	v_mov_b32_e32 v5, s7
	s_add_i32 s4, 0, 0x23910
	ds_write_b128 v1, v[2:5]
	v_mov_b32_e32 v2, s8
	v_mov_b32_e32 v3, s9
	v_mov_b32_e32 v4, s10
	v_mov_b32_e32 v5, s11
	v_mov_b32_e32 v1, s4
	s_add_i32 s4, 0, 0x23920
	ds_write_b128 v1, v[2:5]
	v_mov_b32_e32 v2, s12
	v_mov_b32_e32 v3, s13
	v_mov_b32_e32 v4, s14
	v_mov_b32_e32 v5, s15
	v_mov_b32_e32 v1, s4
	s_add_i32 s4, 0, 0x23930
	ds_write_b128 v1, v[2:5]
	v_mov_b32_e32 v2, s16
	v_mov_b32_e32 v3, s17
	v_mov_b32_e32 v4, s18
	v_mov_b32_e32 v5, s19
	v_mov_b32_e32 v1, s4
	s_add_i32 s4, 0, 0x23940
	ds_write_b128 v1, v[2:5]
	v_mov_b32_e32 v2, s48
	v_mov_b32_e32 v3, s49
	v_mov_b32_e32 v4, s50
	v_mov_b32_e32 v5, s51
	v_mov_b32_e32 v1, s4
	s_add_i32 s4, 0, 0x23950
	ds_write_b128 v1, v[2:5]
	v_mov_b32_e32 v2, s52
	v_mov_b32_e32 v3, s53
	v_mov_b32_e32 v4, s54
	v_mov_b32_e32 v5, s55
	v_mov_b32_e32 v1, s4
	s_add_i32 s4, 0, 0x23960
	ds_write_b128 v1, v[2:5]
	v_mov_b32_e32 v1, s4
	s_load_dwordx16 s[4:19], s[0:1], 0x80
	v_mov_b32_e32 v2, s56
	v_mov_b32_e32 v3, s57
	v_mov_b32_e32 v4, s58
	v_mov_b32_e32 v5, s59
	ds_write_b128 v1, v[2:5]
	v_mov_b32_e32 v2, s60
	v_mov_b32_e32 v3, s61
	v_mov_b32_e32 v4, s62
	v_mov_b32_e32 v5, s63
	v_mov_b32_e32 v1, s20
	ds_write_b128 v1, v[2:5]
	s_waitcnt lgkmcnt(0)
	v_mov_b32_e32 v2, s4
	s_add_i32 s4, 0, 0x23980
	v_mov_b32_e32 v3, s5
	v_mov_b32_e32 v4, s6
	v_mov_b32_e32 v5, s7
	v_mov_b32_e32 v1, s4
	s_add_i32 s4, 0, 0x23990
	ds_write_b128 v1, v[2:5]
	v_mov_b32_e32 v2, s8
	v_mov_b32_e32 v3, s9
	v_mov_b32_e32 v4, s10
	v_mov_b32_e32 v5, s11
	v_mov_b32_e32 v1, s4
	s_add_i32 s4, 0, 0x239a0
	ds_write_b128 v1, v[2:5]
	v_mov_b32_e32 v1, s4
	s_load_dwordx2 s[4:5], s[0:1], 0xc0
	v_mov_b32_e32 v2, s12
	v_mov_b32_e32 v3, s13
	v_mov_b32_e32 v4, s14
	v_mov_b32_e32 v5, s15
	s_add_i32 s6, 0, 0x239b0
	ds_write_b128 v1, v[2:5]
	v_mov_b32_e32 v2, s16
	v_mov_b32_e32 v3, s17
	v_mov_b32_e32 v4, s18
	v_mov_b32_e32 v5, s19
	v_mov_b32_e32 v1, s6
	s_add_i32 s6, 0, 0x239c0
	ds_write_b128 v1, v[2:5]
	v_mov_b32_e32 v1, s6
	s_waitcnt lgkmcnt(0)
	v_mov_b64_e32 v[2:3], s[4:5]
	ds_write_b64 v1, v[2:3]

; #define LAS __attribute__((address_space(3)))
; __device__ __forceinline__ void phase_prologue(const P& p, unsigned char* ws, LAS unsigned char* lds, int wg, int nwg) {
;     ...
;     for (int it = gw; it < DEPTH * I_LAYER; it += NGW) {
;         const int l = it / I_LAYER; int r = it % I_LAYER;
; __device__ __forceinline__ void phase_rec(const P& p, unsigned char* ws, int l, LAS unsigned char* lds, int wg, int nwg) {
;     int lrank = wg, nloop = nwg, srank = wg, nstr = nwg;
;     const bool split = nwg >= 16;
;     if (split) { const int grp = wg >> 3, ngrp = (nwg + 7) >> 3, nlg = (ngrp + 1) >> 1;
;         const int full_l = nlg * 8 - ((ngrp & 1) ? (ngrp * 8 - nwg) : 0), full_s = nwg - full_l;
;         nloop = full_l; nstr = full_s; lrank = (grp >> 1) * 8 + (wg & 7); srank = (grp >> 1) * 8 + (wg & 7);
;         if (grp & 1) lrank = 1 << 30; else srank = 1 << 30; }
;     for (int rl = 0; rl < REP_LOOP; ++rl) for (int tk = lrank; tk < 128; tk += nloop) rec_loop_task(p, ws, l, lds, tk);
.LBB0_1145:
	v_readlane_b32 s0, v248, 27
	s_cmp_gt_u32 s0, 2
	s_cbranch_scc1 .Lcv_skip
	v_readlane_b32 s1, v248, 19
	s_bitcmp1_b32 s1, 3
	s_cbranch_scc0 .Lcv_skip
	s_waitcnt lgkmcnt(0)
	s_barrier
	v_writelane_b32 v251, s3, 0
	v_writelane_b32 v251, s4, 1
	v_writelane_b32 v251, s5, 2
	v_writelane_b32 v251, s6, 3
	v_writelane_b32 v251, s7, 4
	v_writelane_b32 v251, s8, 5
	v_writelane_b32 v251, s9, 6
	v_writelane_b32 v251, s10, 7
	v_writelane_b32 v251, s11, 8
	v_writelane_b32 v251, s12, 9
	v_writelane_b32 v251, s13, 10
	v_writelane_b32 v251, s14, 11
	v_writelane_b32 v251, s15, 12
	v_writelane_b32 v251, s16, 13
	v_writelane_b32 v251, s17, 14
	v_writelane_b32 v251, s18, 15
	v_writelane_b32 v251, s19, 16
	v_writelane_b32 v251, s20, 17
	v_writelane_b32 v251, s21, 18
	v_writelane_b32 v251, s23, 20
	v_writelane_b32 v251, s24, 21
	v_writelane_b32 v251, s25, 22
	v_writelane_b32 v251, s26, 23
	v_writelane_b32 v251, s27, 24
	v_writelane_b32 v251, s28, 25
	v_writelane_b32 v251, s29, 26
	v_writelane_b32 v251, s30, 27
	v_writelane_b32 v251, s31, 28
	v_writelane_b32 v251, s32, 29
	v_writelane_b32 v251, s33, 30
	v_writelane_b32 v251, s34, 31
	v_writelane_b32 v251, s35, 32
	v_writelane_b32 v251, s36, 33
	v_writelane_b32 v251, s37, 34
	v_writelane_b32 v251, s38, 35
	v_writelane_b32 v251, s39, 36
	v_writelane_b32 v251, s40, 37
	v_writelane_b32 v251, s41, 38
	v_writelane_b32 v251, s42, 39
	v_writelane_b32 v251, s43, 40
	v_writelane_b32 v251, s44, 41
	v_writelane_b32 v251, s45, 42
	v_writelane_b32 v251, s46, 43
	v_writelane_b32 v251, s47, 44
	v_writelane_b32 v251, s48, 45
	v_writelane_b32 v251, s49, 46
	v_writelane_b32 v251, s50, 47
	v_writelane_b32 v251, s51, 48
	v_writelane_b32 v251, s52, 49
	v_writelane_b32 v251, s53, 50
	v_writelane_b32 v251, s54, 51
	v_writelane_b32 v251, s55, 52
	v_writelane_b32 v251, s56, 53
	v_writelane_b32 v251, s57, 54
	v_writelane_b32 v251, s58, 55
	v_writelane_b32 v251, s59, 56
	v_writelane_b32 v251, s60, 57
	v_writelane_b32 v251, s61, 58
	v_writelane_b32 v251, s62, 59
	v_writelane_b32 v251, s63, 60
	v_writelane_b32 v251, s64, 61
	v_writelane_b32 v251, s65, 62
	v_writelane_b32 v251, s66, 63
	v_writelane_b32 v252, s67, 0
	v_writelane_b32 v252, s68, 1
	v_writelane_b32 v252, s69, 2
	v_writelane_b32 v252, s70, 3
	v_writelane_b32 v252, s71, 4
	v_writelane_b32 v252, s72, 5
	v_writelane_b32 v252, s73, 6
	v_writelane_b32 v252, s74, 7
	v_writelane_b32 v252, s75, 8
	v_writelane_b32 v252, s76, 9
	v_writelane_b32 v252, s77, 10
	v_writelane_b32 v252, s78, 11
	v_writelane_b32 v252, s79, 12
	v_writelane_b32 v252, s80, 13
	v_writelane_b32 v252, s81, 14
	v_writelane_b32 v252, s82, 15
	v_writelane_b32 v252, s83, 16
	v_writelane_b32 v252, s84, 17
	v_writelane_b32 v252, s85, 18
	v_writelane_b32 v252, s86, 19
	v_writelane_b32 v252, s87, 20
	v_writelane_b32 v252, s88, 21
	v_writelane_b32 v252, s89, 22
	v_writelane_b32 v252, s90, 23
	v_writelane_b32 v252, s91, 24
	v_writelane_b32 v252, s92, 25
	v_writelane_b32 v252, s93, 26
	v_writelane_b32 v252, s94, 27
	v_writelane_b32 v252, s95, 28
	v_writelane_b32 v252, s96, 29
	v_writelane_b32 v252, s97, 30
	v_writelane_b32 v252, s98, 31
	v_writelane_b32 v252, s99, 32
	v_mov_b32_e32 v253, v1
	s_lshr_b32 s22, s1, 4
	s_lshl_b32 s22, s22, 3
	s_and_b32 s1, s1, 7
	s_or_b32 s1, s22, s1
	v_writelane_b32 v250, s1, 4
	s_mul_i32 s22, s0, 0x1400
	s_add_i32 s22, s22, 0x1d700
	v_writelane_b32 v250, s22, 1
	s_add_i32 s22, s22, 0x1400
	v_writelane_b32 v250, s22, 2
	s_add_i32 s22, s22, -1
	v_writelane_b32 v250, s22, 3
	s_mov_b32 s22, 1
	v_writelane_b32 v250, s22, 0
	s_branch .Lcv_entry
